# baseline (speedup 1.0000x reference)
; #define PH(k) if (((PHMASK >> (k)) & 1) && P.ph_lo <= (k) && (k) < P.ph_hi)
; #define SYNC(k) do { if ((k) + 1 < P.ph_hi) { if ((k) == 0) grid.sync(); else xcd_barrier(xb); } } while (0)
; #define REP(b) for (int _rep = 0; _rep < (((REPMASK >> (b)) & 1) ? 2 : 1); ++_rep)
; __global__ __launch_bounds__(512, 2) void mega(Params P) {
;     ...
;     PH(0) { REP(0) phase_prep(P, shm); SYNC(0);
.LBB0_86:
	s_cmp_lt_i32 s93, 2
	s_cbranch_scc1 .LBB0_98

; __device__ __forceinline__ void xcd_barrier(const XcdBarrier& b) {
;     asm volatile("s_waitcnt vmcnt(0)" ::: "memory");
;     __syncthreads();
;     if (threadIdx.x == 0) {
	s_waitcnt vmcnt(0)
	s_barrier
	s_mov_b64 s[0:1], exec
	v_readlane_b32 s4, v248, 4
	v_readlane_b32 s5, v248, 5
	s_and_b64 s[4:5], s[0:1], s[4:5]
	s_mov_b64 exec, s[4:5]
	s_cbranch_execz .Lsy0_202

; __device__ __forceinline__ void xcd_barrier(const XcdBarrier& b) {
;     ...
;         __builtin_amdgcn_s_waitcnt(0);
;         unsigned nloc = b.st[0], nx = b.st[1];
;         if (nloc == 0u) { xcd_barrier_complete(bar, b.x, nloc, nx); b.st[0] = nloc; b.st[1] = nx; }
	s_add_i32 s3, 0, 0x24800
	v_mov_b32_e32 v0, s3
	s_waitcnt vmcnt(0) expcnt(0) lgkmcnt(0)
	ds_read_b32 v2, v0
	s_add_i32 s3, 0, 0x24804
	v_mov_b32_e32 v0, s3
	ds_read_b32 v0, v0
	s_waitcnt lgkmcnt(1)
	v_cmp_ne_u32_e32 vcc, 0, v2
	s_cbranch_vccnz .Lsy0_166

; __device__ __forceinline__ unsigned xb_ld(unsigned* p)              { return __hip_atomic_load(p, __ATOMIC_RELAXED, __HIP_MEMORY_SCOPE_AGENT); }
; __device__ __forceinline__ void xcd_barrier_complete(unsigned* bar, unsigned x, unsigned& nloc, unsigned& nx) {
;     const unsigned G = gridDim.x * gridDim.y * gridDim.z;
;     unsigned sum, cnt, mine, sp = 0u;
;     for (;;) {
;         sum = 0u; cnt = 0u; mine = 0u;
; #pragma unroll
;         for (unsigned j = 0; j < 16; ++j) { const unsigned c = xb_ld(&bar[XB_XCNT(j)]); sum += c; cnt += (c > 0u) ? 1u : 0u; mine = (j == x) ? c : mine; }
	s_add_u32 s4, s90, 0x5880200
	s_addc_u32 s5, s91, 0
	s_add_u32 s6, s90, 0x5880400
	s_addc_u32 s7, s91, 0
	s_add_u32 s8, s90, 0x5880500
	s_addc_u32 s9, s91, 0
	s_add_u32 s10, s90, 0x5880600
	s_addc_u32 s11, s91, 0
	s_add_u32 s12, s90, 0x5880700
	s_addc_u32 s13, s91, 0
	s_add_u32 s14, s90, 0x5880800
	s_addc_u32 s15, s91, 0
	s_add_u32 s16, s90, 0x5880900
	s_addc_u32 s17, s91, 0
	s_add_u32 s18, s90, 0x5880a00
	s_addc_u32 s19, s91, 0
	s_add_u32 s20, s90, 0x5880b00
	s_addc_u32 s21, s91, 0
	s_add_u32 s22, s90, 0x5880c00
	s_addc_u32 s23, s91, 0
	s_add_u32 s24, s90, 0x5880d00
	s_addc_u32 s25, s91, 0
	s_add_u32 s26, s90, 0x5880e00
	s_addc_u32 s27, s91, 0
	s_add_u32 s40, s90, 0x5880f00
	s_addc_u32 s41, s91, 0
	s_add_u32 s42, s90, 0x5881000
	s_addc_u32 s43, s91, 0
	s_add_u32 s44, s90, 0x5881100
	s_addc_u32 s45, s91, 0
	s_add_u32 s46, s90, 0x5881200
	v_readlane_b32 s3, v248, 0
	s_addc_u32 s47, s91, 0
	s_mul_i32 s3, s95, s3
	s_add_u32 s48, s90, 0x5881300
	s_mul_i32 s3, s3, s94
	s_addc_u32 s49, s91, 0
	s_mov_b32 s60, 1
	v_mov_b32_e32 v16, 0
	s_branch .Lsy0_154

; __device__ __forceinline__ unsigned xb_ld(unsigned* p)              { return __hip_atomic_load(p, __ATOMIC_RELAXED, __HIP_MEMORY_SCOPE_AGENT); }
; __device__ __forceinline__ void xcd_barrier_complete(unsigned* bar, unsigned x, unsigned& nloc, unsigned& nx) {
;     ...
;     for (;;) {
;         sum = 0u; cnt = 0u; mine = 0u;
; #pragma unroll
;         for (unsigned j = 0; j < 16; ++j) { const unsigned c = xb_ld(&bar[XB_XCNT(j)]); sum += c; cnt += (c > 0u) ? 1u : 0u; mine = (j == x) ? c : mine; }
;         if (sum == G) break;
.Lsy0_154:
	global_load_dword v15, v16, s[6:7] sc1
	s_waitcnt lgkmcnt(0)
	global_load_dword v0, v16, s[8:9] sc1
	global_load_dword v1, v16, s[10:11] sc1
	global_load_dword v2, v16, s[12:13] sc1
	global_load_dword v3, v16, s[14:15] sc1
	global_load_dword v4, v16, s[16:17] sc1
	global_load_dword v5, v16, s[18:19] sc1
	global_load_dword v6, v16, s[20:21] sc1
	global_load_dword v7, v16, s[22:23] sc1
	global_load_dword v8, v16, s[24:25] sc1
	global_load_dword v9, v16, s[26:27] sc1
	global_load_dword v10, v16, s[40:41] sc1
	global_load_dword v11, v16, s[42:43] sc1
	global_load_dword v12, v16, s[44:45] sc1
	global_load_dword v13, v16, s[46:47] sc1
	global_load_dword v14, v16, s[48:49] sc1
	s_mov_b64 s[50:51], -1
	s_mov_b64 s[56:57], -1
	s_waitcnt vmcnt(14)
	v_add_u32_e32 v17, v0, v15
	s_waitcnt vmcnt(13)
	v_add_u32_e32 v17, v17, v1
	s_waitcnt vmcnt(12)
	v_add_u32_e32 v17, v17, v2
	s_waitcnt vmcnt(11)
	v_add_u32_e32 v17, v17, v3
	s_waitcnt vmcnt(10)
	v_add_u32_e32 v17, v17, v4
	s_waitcnt vmcnt(9)
	v_add_u32_e32 v17, v17, v5
	s_waitcnt vmcnt(8)
	v_add_u32_e32 v17, v17, v6
	s_waitcnt vmcnt(7)
	v_add_u32_e32 v17, v17, v7
	s_waitcnt vmcnt(6)
	v_add_u32_e32 v17, v17, v8
	s_waitcnt vmcnt(5)
	v_add_u32_e32 v17, v17, v9
	s_waitcnt vmcnt(4)
	v_add_u32_e32 v17, v17, v10
	s_waitcnt vmcnt(3)
	v_add_u32_e32 v17, v17, v11
	s_waitcnt vmcnt(2)
	v_add_u32_e32 v17, v17, v12
	s_waitcnt vmcnt(1)
	v_add_u32_e32 v17, v17, v13
	s_waitcnt vmcnt(0)
	v_add_u32_e32 v17, v17, v14
	v_cmp_eq_u32_e32 vcc, s3, v17
	s_cbranch_vccnz .Lsy0_153

; __device__ __forceinline__ unsigned xb_ld(unsigned* p)              { return __hip_atomic_load(p, __ATOMIC_RELAXED, __HIP_MEMORY_SCOPE_AGENT); }
; __device__ __forceinline__ void xcd_barrier_complete(unsigned* bar, unsigned x, unsigned& nloc, unsigned& nx) {
;     ...
;         __builtin_amdgcn_s_sleep(1);
;         if ((++sp & 255u) == 0u) { if (xb_ld(&bar[XB_TMO])) break; if (sp > XB_SPIN_CAP) { atomicAdd(&bar[XB_TMO], 1u); break; } }
	s_and_b32 s30, s60, 0xff
	s_cmp_eq_u32 s30, 0
	s_mov_b64 s[58:59], -1
	s_sleep 1
	s_cbranch_scc0 .Lsy0_158

; __device__ __forceinline__ unsigned xb_ld(unsigned* p)              { return __hip_atomic_load(p, __ATOMIC_RELAXED, __HIP_MEMORY_SCOPE_AGENT); }
; __device__ __forceinline__ void xcd_barrier_complete(unsigned* bar, unsigned x, unsigned& nloc, unsigned& nx) {
;     ...
;         if ((++sp & 255u) == 0u) { if (xb_ld(&bar[XB_TMO])) break; if (sp > XB_SPIN_CAP) { atomicAdd(&bar[XB_TMO], 1u); break; } }
	global_load_dword v17, v16, s[4:5] sc1
	s_waitcnt vmcnt(0)
	v_cmp_eq_u32_e32 vcc, 0, v17
	s_cbranch_vccnz .Lsy0_160

; __device__ __forceinline__ unsigned xb_ld(unsigned* p)              { return __hip_atomic_load(p, __ATOMIC_RELAXED, __HIP_MEMORY_SCOPE_AGENT); }
; __device__ __forceinline__ void xcd_barrier_complete(unsigned* bar, unsigned x, unsigned& nloc, unsigned& nx) {
;     ...
;         if ((++sp & 255u) == 0u) { if (xb_ld(&bar[XB_TMO])) break; if (sp > XB_SPIN_CAP) { atomicAdd(&bar[XB_TMO], 1u); break; } }
	s_mov_b64 s[58:59], 0

; __device__ __forceinline__ unsigned xb_ld(unsigned* p)              { return __hip_atomic_load(p, __ATOMIC_RELAXED, __HIP_MEMORY_SCOPE_AGENT); }
; __device__ __forceinline__ void xcd_barrier_complete(unsigned* bar, unsigned x, unsigned& nloc, unsigned& nx) {
;     ...
;         if ((++sp & 255u) == 0u) { if (xb_ld(&bar[XB_TMO])) break; if (sp > XB_SPIN_CAP) { atomicAdd(&bar[XB_TMO], 1u); break; } }
.Lsy0_161:
	s_andn2_b64 vcc, exec, s[50:51]
	s_cbranch_vccz .Lsy0_165

; __device__ __forceinline__ unsigned xb_ld(unsigned* p)              { return __hip_atomic_load(p, __ATOMIC_RELAXED, __HIP_MEMORY_SCOPE_AGENT); }
; __device__ __forceinline__ void xcd_barrier_complete(unsigned* bar, unsigned x, unsigned& nloc, unsigned& nx) {
;     ...
;         if ((++sp & 255u) == 0u) { if (xb_ld(&bar[XB_TMO])) break; if (sp > XB_SPIN_CAP) { atomicAdd(&bar[XB_TMO], 1u); break; } }
	s_mov_b64 s[8:9], exec
	v_mbcnt_lo_u32_b32 v16, s8, 0
	v_mbcnt_hi_u32_b32 v16, s9, v16
	v_cmp_eq_u32_e32 vcc, 0, v16
	s_and_saveexec_b64 s[6:7], vcc
	s_cbranch_execz .Lsy0_164

; __device__ __forceinline__ unsigned xb_ld(unsigned* p)              { return __hip_atomic_load(p, __ATOMIC_RELAXED, __HIP_MEMORY_SCOPE_AGENT); }
; __device__ __forceinline__ void xcd_barrier_complete(unsigned* bar, unsigned x, unsigned& nloc, unsigned& nx) {
;     ...
;         if ((++sp & 255u) == 0u) { if (xb_ld(&bar[XB_TMO])) break; if (sp > XB_SPIN_CAP) { atomicAdd(&bar[XB_TMO], 1u); break; } }
	s_bcnt1_i32_b64 s3, s[8:9]
	v_mov_b32_e32 v16, 0
	v_mov_b32_e32 v17, s3
	global_atomic_add v16, v17, s[4:5]

; __device__ __forceinline__ unsigned xb_add(unsigned* p, unsigned v) { return __hip_atomic_fetch_add(p, v, __ATOMIC_RELAXED, __HIP_MEMORY_SCOPE_AGENT); }
; __device__ __forceinline__ void xcd_barrier(const XcdBarrier& b) {
;     ...
;         if (nloc == 0u) { xcd_barrier_complete(bar, b.x, nloc, nx); b.st[0] = nloc; b.st[1] = nx; }
;         const unsigned old = xb_add(&bar[XB_XSUB(b.x)], 1u);
.Lsy0_166:
	s_mov_b64 s[6:7], exec
	v_readlane_b32 s3, v248, 3
	s_lshl_b32 s3, s3, 8
	v_mbcnt_lo_u32_b32 v1, s6, 0
	s_add_u32 s4, s96, s3
	v_mbcnt_hi_u32_b32 v1, s7, v1
	s_addc_u32 s5, s97, 0
	v_cmp_eq_u32_e32 vcc, 0, v1

; __device__ __forceinline__ unsigned xb_add(unsigned* p, unsigned v) { return __hip_atomic_fetch_add(p, v, __ATOMIC_RELAXED, __HIP_MEMORY_SCOPE_AGENT); }
; __device__ __forceinline__ void xcd_barrier(const XcdBarrier& b) {
;     ...
;         const unsigned old = xb_add(&bar[XB_XSUB(b.x)], 1u);
	s_and_saveexec_b64 s[8:9], vcc
	s_cbranch_execz .Lsy0_168

; __device__ __forceinline__ unsigned xb_add(unsigned* p, unsigned v) { return __hip_atomic_fetch_add(p, v, __ATOMIC_RELAXED, __HIP_MEMORY_SCOPE_AGENT); }
; __device__ __forceinline__ void xcd_barrier(const XcdBarrier& b) {
;     ...
;         const unsigned old = xb_add(&bar[XB_XSUB(b.x)], 1u);
;         const unsigned gen = old / nloc;
;         if (old + 1u == (gen + 1u) * nloc) {
	s_bcnt1_i32_b64 s3, s[6:7]
	v_mov_b32_e32 v3, 0x1000
	v_mov_b32_e32 v4, s3
	global_atomic_add v3, v3, v4, s[4:5] offset:1024 sc0
.Lsy0_168:
	s_or_b64 exec, exec, s[8:9]
	v_cvt_f32_u32_e32 v4, v2
	s_waitcnt vmcnt(0)
	v_readfirstlane_b32 s3, v3
	v_sub_u32_e32 v3, 0, v2
	v_rcp_iflag_f32_e32 v4, v4
	v_add_u32_e32 v5, s3, v1
	v_mul_f32_e32 v4, 0x4f7ffffe, v4
	v_cvt_u32_f32_e32 v4, v4
	v_mul_lo_u32 v1, v3, v4
	v_mul_hi_u32 v1, v4, v1
	v_add_u32_e32 v1, v4, v1
	v_mul_hi_u32 v1, v5, v1
	v_mul_lo_u32 v3, v1, v2
	v_sub_u32_e32 v3, v5, v3
	v_add_u32_e32 v4, 1, v1
	v_cmp_ge_u32_e32 vcc, v3, v2
	s_nop 1
	v_cndmask_b32_e32 v1, v1, v4, vcc
	v_sub_u32_e32 v4, v3, v2
	v_cndmask_b32_e32 v3, v3, v4, vcc
	v_add_u32_e32 v4, 1, v1
	v_cmp_ge_u32_e32 vcc, v3, v2
	v_add_u32_e32 v3, 1, v5
	s_nop 0
	v_cndmask_b32_e32 v1, v1, v4, vcc
	v_mul_lo_u32 v4, v2, v1
	v_add_u32_e32 v2, v4, v2
	v_cmp_ne_u32_e32 vcc, v3, v2
	s_and_saveexec_b64 s[6:7], vcc
	s_xor_b64 s[6:7], exec, s[6:7]
	s_cbranch_execz .Lsy0_182

; __device__ __forceinline__ unsigned xb_ld(unsigned* p)              { return __hip_atomic_load(p, __ATOMIC_RELAXED, __HIP_MEMORY_SCOPE_AGENT); }
; #define XB_SPIN(cond, bar) do { unsigned _sp = 0; while (cond) { __builtin_amdgcn_s_sleep(1); \
;     if ((++_sp & 255u) == 0u) { if (xb_ld(&(bar)[XB_TMO])) break; if (_sp > XB_SPIN_CAP) { atomicAdd(&(bar)[XB_TMO], 1u); break; } } } } while (0)
; __device__ __forceinline__ void xcd_barrier(const XcdBarrier& b) {
;     ...
;             XB_SPIN(xb_ld(&bar[XB_XGEN(b.x)]) == gen, bar);
	s_waitcnt lgkmcnt(0)
	v_mov_b32_e32 v0, 0x2000
	global_load_dword v0, v0, s[4:5] offset:1024 sc1
	s_add_u32 s12, s4, 0x2400
	s_addc_u32 s13, s5, 0
	s_waitcnt vmcnt(0)
	v_cmp_eq_u32_e32 vcc, v0, v1
	s_and_saveexec_b64 s[8:9], vcc
	s_cbranch_execz .Lsy0_181

; __device__ __forceinline__ unsigned xb_ld(unsigned* p)              { return __hip_atomic_load(p, __ATOMIC_RELAXED, __HIP_MEMORY_SCOPE_AGENT); }
; #define XB_SPIN(cond, bar) do { unsigned _sp = 0; while (cond) { __builtin_amdgcn_s_sleep(1); \
;     if ((++_sp & 255u) == 0u) { if (xb_ld(&(bar)[XB_TMO])) break; if (_sp > XB_SPIN_CAP) { atomicAdd(&(bar)[XB_TMO], 1u); break; } } } } while (0)
; __device__ __forceinline__ void xcd_barrier(const XcdBarrier& b) {
;     ...
;             XB_SPIN(xb_ld(&bar[XB_XGEN(b.x)]) == gen, bar);
	s_add_u32 s10, s90, 0x5880200
	s_addc_u32 s11, s91, 0
	s_mov_b32 s3, 1
	s_mov_b64 s[14:15], 0
	v_mov_b32_e32 v0, 0

	s_branch .Lsy0_172

.Lsy0_172:
	s_and_b32 s20, s3, 0xff
	s_mov_b64 s[18:19], -1
	s_cmp_lg_u32 s20, 0
	s_mov_b64 s[22:23], -1
	s_sleep 1

	s_cbranch_scc1 .Lsy0_175

	global_load_dword v2, v0, s[10:11] sc1
	s_waitcnt vmcnt(0)
	v_cmp_eq_u32_e32 vcc, 0, v2
	s_cbranch_vccnz .Lsy0_177

	s_mov_b64 s[22:23], 0
	s_mov_b64 s[20:21], -1

.Lsy0_178:
	s_or_b64 exec, exec, s[14:15]
	s_xor_b64 s[12:13], s[16:17], -1
	s_and_saveexec_b64 s[14:15], s[12:13]
	s_xor_b64 s[14:15], exec, s[14:15]
	s_cbranch_execz .Lsy0_181

	s_mov_b64 s[12:13], exec
	v_mbcnt_lo_u32_b32 v0, s12, 0
	v_mbcnt_hi_u32_b32 v0, s13, v0
	v_cmp_eq_u32_e32 vcc, 0, v0
	s_and_b64 s[14:15], exec, vcc
	s_mov_b64 exec, s[14:15]
	s_cbranch_execz .Lsy0_181

; __device__ __forceinline__ void xcd_barrier(const XcdBarrier& b) {
;     ...
;             __builtin_amdgcn_fence(__ATOMIC_ACQUIRE, "agent");
;             asm volatile("s_waitcnt vmcnt(0)" ::: "memory");
	s_bcnt1_i32_b64 s3, s[12:13]
	v_mov_b32_e32 v0, 0
	v_mov_b32_e32 v1, s3
	global_atomic_add v0, v1, s[10:11]
.Lsy0_181:
	s_or_b64 exec, exec, s[8:9]
	s_waitcnt vmcnt(0)
	buffer_inv sc1
	s_waitcnt vmcnt(0)

; __device__ __forceinline__ void xcd_barrier(const XcdBarrier& b) {
;     ...
;         if (old + 1u == (gen + 1u) * nloc) {
;             __builtin_amdgcn_fence(__ATOMIC_RELEASE, "agent");
.Lsy0_182:
	s_andn2_saveexec_b64 s[6:7], s[6:7]
	s_cbranch_execz .Lsy0_202

; __device__ __forceinline__ unsigned xb_add(unsigned* p, unsigned v) { return __hip_atomic_fetch_add(p, v, __ATOMIC_RELAXED, __HIP_MEMORY_SCOPE_AGENT); }
; __device__ __forceinline__ void xcd_barrier(const XcdBarrier& b) {
;     ...
;             __builtin_amdgcn_fence(__ATOMIC_RELEASE, "agent");
;             asm volatile("s_waitcnt vmcnt(0)" ::: "memory");
;             const unsigned og = xb_add(&bar[XB_TOP], 1u);
	s_mov_b64 s[6:7], exec
	buffer_wbl2 sc1
	s_waitcnt lgkmcnt(0)
	s_waitcnt vmcnt(0)
	v_mbcnt_lo_u32_b32 v1, s6, 0
	v_mbcnt_hi_u32_b32 v1, s7, v1
	v_cmp_eq_u32_e32 vcc, 0, v1

; __device__ __forceinline__ unsigned xb_add(unsigned* p, unsigned v) { return __hip_atomic_fetch_add(p, v, __ATOMIC_RELAXED, __HIP_MEMORY_SCOPE_AGENT); }
; __device__ __forceinline__ void xcd_barrier(const XcdBarrier& b) {
;     ...
;             const unsigned og = xb_add(&bar[XB_TOP], 1u);
	s_and_saveexec_b64 s[8:9], vcc
	s_cbranch_execz .Lsy0_185

; __device__ __forceinline__ unsigned xb_ld(unsigned* p)              { return __hip_atomic_load(p, __ATOMIC_RELAXED, __HIP_MEMORY_SCOPE_AGENT); }
; __device__ __forceinline__ unsigned xb_add(unsigned* p, unsigned v) { return __hip_atomic_fetch_add(p, v, __ATOMIC_RELAXED, __HIP_MEMORY_SCOPE_AGENT); }
; #define XB_SPIN(cond, bar) do { unsigned _sp = 0; while (cond) { __builtin_amdgcn_s_sleep(1); \
;     if ((++_sp & 255u) == 0u) { if (xb_ld(&(bar)[XB_TMO])) break; if (_sp > XB_SPIN_CAP) { atomicAdd(&(bar)[XB_TMO], 1u); break; } } } } while (0)
; __device__ __forceinline__ void xcd_barrier(const XcdBarrier& b) {
;     ...
;             const unsigned og = xb_add(&bar[XB_TOP], 1u);
;             const unsigned tg = og / nx;
;             if (og + 1u == (tg + 1u) * nx) xb_add(&bar[XB_TOPGEN], 1u);
;             else XB_SPIN(xb_ld(&bar[XB_TOPGEN]) == tg, bar);
	s_bcnt1_i32_b64 s3, s[6:7]
	v_mov_b32_e32 v2, 0x5883000
	v_mov_b32_e32 v3, s3
	global_atomic_add v2, v2, v3, s[90:91] offset:1024 sc0
.Lsy0_185:
	s_or_b64 exec, exec, s[8:9]
	v_cvt_f32_u32_e32 v3, v0
	s_waitcnt vmcnt(0)
	v_readfirstlane_b32 s3, v2
	s_add_u32 s8, s90, 0x5883500
	s_addc_u32 s9, s91, 0
	v_rcp_iflag_f32_e32 v3, v3
	v_add_u32_e32 v1, s3, v1
	v_add_u32_e32 v4, 1, v1
	s_mov_b64 s[10:11], -1
	v_mul_f32_e32 v2, 0x4f7ffffe, v3
	v_cvt_u32_f32_e32 v2, v2
	v_sub_u32_e32 v3, 0, v0
	v_mul_lo_u32 v3, v3, v2
	v_mul_hi_u32 v3, v2, v3
	v_add_u32_e32 v2, v2, v3
	v_mul_hi_u32 v2, v1, v2
	v_mul_lo_u32 v3, v2, v0
	v_sub_u32_e32 v1, v1, v3
	v_add_u32_e32 v5, 1, v2
	v_cmp_ge_u32_e32 vcc, v1, v0
	v_sub_u32_e32 v3, v1, v0
	s_nop 0
	v_cndmask_b32_e32 v2, v2, v5, vcc
	v_cndmask_b32_e32 v1, v1, v3, vcc
	v_add_u32_e32 v3, 1, v2
	v_cmp_ge_u32_e32 vcc, v1, v0
	s_nop 1
	v_cndmask_b32_e32 v2, v2, v3, vcc
	v_mul_lo_u32 v1, v0, v2
	v_add_u32_e32 v0, v1, v0
	v_cmp_ne_u32_e32 vcc, v4, v0
	v_mov_b64_e32 v[0:1], s[8:9]
	s_and_saveexec_b64 s[6:7], vcc
	s_cbranch_execz .Lsy0_197

; __device__ __forceinline__ unsigned xb_ld(unsigned* p)              { return __hip_atomic_load(p, __ATOMIC_RELAXED, __HIP_MEMORY_SCOPE_AGENT); }
; #define XB_SPIN(cond, bar) do { unsigned _sp = 0; while (cond) { __builtin_amdgcn_s_sleep(1); \
;     if ((++_sp & 255u) == 0u) { if (xb_ld(&(bar)[XB_TMO])) break; if (_sp > XB_SPIN_CAP) { atomicAdd(&(bar)[XB_TMO], 1u); break; } } } } while (0)
; __device__ __forceinline__ void xcd_barrier(const XcdBarrier& b) {
;     ...
;             else XB_SPIN(xb_ld(&bar[XB_TOPGEN]) == tg, bar);
	v_mov_b32_e32 v0, 0
	global_load_dword v1, v0, s[8:9] sc1
	s_mov_b64 s[14:15], 0

; __device__ __forceinline__ unsigned xb_ld(unsigned* p)              { return __hip_atomic_load(p, __ATOMIC_RELAXED, __HIP_MEMORY_SCOPE_AGENT); }
; #define XB_SPIN(cond, bar) do { unsigned _sp = 0; while (cond) { __builtin_amdgcn_s_sleep(1); \
;     if ((++_sp & 255u) == 0u) { if (xb_ld(&(bar)[XB_TMO])) break; if (_sp > XB_SPIN_CAP) { atomicAdd(&(bar)[XB_TMO], 1u); break; } } } } while (0)
; __device__ __forceinline__ void xcd_barrier(const XcdBarrier& b) {
;     ...
;             else XB_SPIN(xb_ld(&bar[XB_TOPGEN]) == tg, bar);
	s_waitcnt vmcnt(0)
	v_cmp_eq_u32_e32 vcc, v1, v2
	s_and_saveexec_b64 s[12:13], vcc
	s_cbranch_execz .Lsy0_196

; __device__ __forceinline__ unsigned xb_ld(unsigned* p)              { return __hip_atomic_load(p, __ATOMIC_RELAXED, __HIP_MEMORY_SCOPE_AGENT); }
; #define XB_SPIN(cond, bar) do { unsigned _sp = 0; while (cond) { __builtin_amdgcn_s_sleep(1); \
;     if ((++_sp & 255u) == 0u) { if (xb_ld(&(bar)[XB_TMO])) break; if (_sp > XB_SPIN_CAP) { atomicAdd(&(bar)[XB_TMO], 1u); break; } } } } while (0)
; __device__ __forceinline__ void xcd_barrier(const XcdBarrier& b) {
;     ...
;             else XB_SPIN(xb_ld(&bar[XB_TOPGEN]) == tg, bar);
	s_add_u32 s10, s90, 0x5880200
	s_addc_u32 s11, s91, 0
	s_mov_b32 s3, 1

	s_branch .Lsy0_189

.Lsy0_189:
	s_and_b32 s18, s3, 0xff
	s_cmp_lg_u32 s18, 0
	s_mov_b64 s[20:21], -1
	s_sleep 1

	s_cbranch_scc1 .Lsy0_192

	global_load_dword v1, v0, s[10:11] sc1
	s_waitcnt vmcnt(0)
	v_cmp_eq_u32_e32 vcc, 0, v1
	s_cbranch_vccnz .Lsy0_194

	s_mov_b64 s[20:21], 0
	s_mov_b64 s[18:19], -1

; __device__ __forceinline__ unsigned xb_add(unsigned* p, unsigned v) { return __hip_atomic_fetch_add(p, v, __ATOMIC_RELAXED, __HIP_MEMORY_SCOPE_AGENT); }
; __device__ __forceinline__ void xcd_barrier(const XcdBarrier& b) {
;     ...
;             if (og + 1u == (tg + 1u) * nx) xb_add(&bar[XB_TOPGEN], 1u);
.Lsy0_197:
	s_or_b64 exec, exec, s[6:7]
	s_and_saveexec_b64 s[6:7], s[10:11]
	s_cbranch_execz .Lsy0_199

; __device__ __forceinline__ unsigned xb_ld(unsigned* p)              { return __hip_atomic_load(p, __ATOMIC_RELAXED, __HIP_MEMORY_SCOPE_AGENT); }
; __device__ __forceinline__ unsigned xb_add(unsigned* p, unsigned v) { return __hip_atomic_fetch_add(p, v, __ATOMIC_RELAXED, __HIP_MEMORY_SCOPE_AGENT); }
; #define XB_SPIN(cond, bar) do { unsigned _sp = 0; while (cond) { __builtin_amdgcn_s_sleep(1); \
;     if ((++_sp & 255u) == 0u) { if (xb_ld(&(bar)[XB_TMO])) break; if (_sp > XB_SPIN_CAP) { atomicAdd(&(bar)[XB_TMO], 1u); break; } } } } while (0)
; __device__ __forceinline__ void xcd_barrier(const XcdBarrier& b) {
;     ...
;             if (og + 1u == (tg + 1u) * nx) xb_add(&bar[XB_TOPGEN], 1u);
;             else XB_SPIN(xb_ld(&bar[XB_TOPGEN]) == tg, bar);
;             __builtin_amdgcn_fence(__ATOMIC_ACQUIRE, "agent");
;             xb_add(&bar[XB_XGEN(b.x)], 1u);
	v_mov_b32_e32 v2, 1
	global_atomic_add v[0:1], v2, off
.Lsy0_199:
	s_or_b64 exec, exec, s[6:7]
	s_mov_b64 s[6:7], exec
	v_mbcnt_lo_u32_b32 v0, s6, 0
	v_mbcnt_hi_u32_b32 v0, s7, v0
	v_cmp_eq_u32_e32 vcc, 0, v0
	s_waitcnt vmcnt(0)
	buffer_inv sc1
	s_and_saveexec_b64 s[8:9], vcc
	s_cbranch_execz .Lsy0_201

; __device__ __forceinline__ unsigned xb_add(unsigned* p, unsigned v) { return __hip_atomic_fetch_add(p, v, __ATOMIC_RELAXED, __HIP_MEMORY_SCOPE_AGENT); }
; __device__ __forceinline__ void xcd_barrier(const XcdBarrier& b) {
;     ...
;             xb_add(&bar[XB_XGEN(b.x)], 1u);
	s_bcnt1_i32_b64 s3, s[6:7]
	v_mov_b32_e32 v0, 0x2000
	v_mov_b32_e32 v1, s3
	global_atomic_add v0, v1, s[4:5] offset:1024

; template <class Epi, class Sched>
; __device__ __forceinline__ void gemm_phase(PG8_LAS unsigned char* lds, const Gemm g, const Sched& S, const Epi& E) {
;     const int tid = threadIdx.x, wid = __builtin_amdgcn_readfirstlane(tid >> 6), lane = tid & 63, wr = wid >> 2, wc = wid & 3, fr = lane & 15, fq = lane >> 4;
;     const int K = g.K, nt = K / BK;
;     unsigned voffA[2], voffB[2];
; #pragma unroll
;     for (int i = 0; i < 2; ++i) { int R, C; stage_rc(tid * 16 + i * 8192, R, C); const int Rb = Epi::PERM ? ((R & ~31) + perm32(R & 31)) : R;
;         voffA[i] = (unsigned)(R * K + C) * 2u; voffB[i] = (unsigned)(Rb * K + C) * 2u; }
;     const size_t kstep = (size_t)(BK * 2);
;     const size_t hstep = (size_t)HALF * K * 2;
;     const size_t tstep = 2 * hstep;
;     const unsigned ldsw = (unsigned)wid * 1024u;
;     const int aoff = lds_byte(wr * 64 + fr, fq * 8), boff = lds_byte(wc * 32 + fr, fq * 8);
; __device__ __forceinline__ void xcd_barrier(const XcdBarrier& b) {
;     ...
;     }
;     __syncthreads();
.Lsy0_202:
	s_or_b64 exec, exec, s[0:1]
	s_waitcnt lgkmcnt(0)
	s_barrier
.LBB0_98:
	s_add_u32 s36, s90, 0xe000000
	s_addc_u32 s37, s91, 0
	s_cmp_lt_i32 s92, 2
	s_cselect_b64 s[0:1], -1, 0
	s_cmp_gt_i32 s93, 1
	s_cselect_b64 s[4:5], -1, 0
	s_and_b64 s[0:1], s[0:1], s[4:5]
	s_andn2_b64 vcc, exec, s[0:1]
	s_cbranch_vccnz .LBB0_203
	v_lshrrev_b32_e32 v2, 5, v144
	v_lshrrev_b32_e32 v4, 1, v144
	v_and_b32_e32 v2, 4, v2
	v_bfe_u32 v3, v144, 2, 2
	v_and_b32_e32 v143, 24, v4
	v_lshlrev_b32_e32 v0, 4, v144
	v_and_b32_e32 v1, 32, v144
	v_bfe_u32 v142, v144, 2, 4
	v_or3_b32 v2, v2, v3, v143
	v_lshrrev_b32_e32 v3, 3, v144
	s_movk_i32 s0, 0x70
	v_bitop3_b32 v140, v0, v1, 48 bitop3:0x6c
	v_and_b32_e32 v141, 64, v144
	v_and_or_b32 v4, v3, s0, v142
	s_movk_i32 s0, 0x60
	v_add_u32_e32 v145, 0x2000, v0
	v_or_b32_e32 v1, v140, v141
	v_and_or_b32 v3, v3, s0, v2
	v_lshrrev_b32_e32 v0, 7, v145
	s_movk_i32 s0, 0xf0
	v_lshl_or_b32 v150, v3, 12, v1
	v_and_or_b32 v3, v0, s0, v142
	s_movk_i32 s0, 0xe0
	v_and_or_b32 v0, v0, s0, v2
	v_lshl_or_b32 v148, v4, 12, v1
	v_lshl_or_b32 v152, v3, 12, v1
	v_lshl_or_b32 v154, v0, 12, v1
	v_lshlrev_b32_e32 v0, 6, v144
	v_lshlrev_b32_e32 v1, 2, v144
	v_lshlrev_b32_e32 v156, 1, v143
	v_and_b32_e32 v0, 0x3c0, v0
	v_and_b32_e32 v1, 32, v1
	v_readfirstlane_b32 s3, v144
	v_and_b32_e32 v147, 15, v144
	s_cmpk_gt_i32 s2, 0x7ff
	v_bitop3_b32 v157, v156, v1, v0 bitop3:0x36
	s_cbranch_scc1 .LBB0_129
	s_ashr_i32 s26, s2, 31
	s_lshr_b32 s0, s26, 29
	s_add_i32 s4, s2, s0
	s_and_b32 s0, s4, -8
	s_sub_i32 s5, s2, s0
	s_cmp_gt_i32 s5, -1
	s_cbranch_scc0 .LBB0_102
	s_lshl_b32 s6, s5, 8
	s_cbranch_execz .LBB0_103
	s_branch .LBB0_104
